# diff-attention finalize: 16 row-sum all-reduces done with in-place DPP adds (xor 1,2,4,8) + one bpermute step each, instead of 80 serialized ds_bpermute round trips
# baseline (speedup 1.0000x reference)
; __device__ __forceinline__ void diff_unit(const Params& P, int l, int b, int h, int qb, float lam, float lam_init, LAS unsigned char* lds, bool dry = false) {
;     ...
;         for (int d = 0; d < 4; ++d)
; #pragma unroll
;             for (int r = 0; r < 16; ++r) { const float v = o[d][r] * il[r] - xch[((wq * 4 + d) * 16 + r) * 64 + lane]; o[d][r] = v; ssq[r] += v * v; }
.LBB0_491:
	s_cmpk_gt_u32 s73, 0xff
	s_waitcnt lgkmcnt(0)
	s_barrier
	s_cbranch_scc1 .LBB0_493
	s_add_i32 s2, 0, 0x13800
	v_lshl_add_u32 v105, v1, 2, s2
	s_lshl_b32 s2, s73, 8
	s_and_b32 s3, s2, 0xc000
	v_add_u32_e32 v106, s3, v105
	ds_read2st64_b32 v[34:35], v106 offset1:1
	s_or_b32 s2, s2, 0x3f00
	v_readlane_b32 s8, v254, 29
	v_readlane_b32 s20, v254, 41
	v_readlane_b32 s21, v254, 42
	s_waitcnt lgkmcnt(0)
	v_fma_f32 v89, v52, v80, -v34
	v_fma_f32 v88, v53, v81, -v35
	ds_read2st64_b32 v[34:35], v106 offset0:2 offset1:3
	v_readlane_b32 s9, v254, 30
	v_readlane_b32 s10, v254, 31
	v_readlane_b32 s11, v254, 32
	v_readlane_b32 s12, v254, 33
	s_waitcnt lgkmcnt(0)
	v_fma_f32 v87, v54, v82, -v34
	v_fma_f32 v86, v55, v83, -v35
	ds_read2st64_b32 v[34:35], v106 offset0:4 offset1:5
	v_readlane_b32 s13, v254, 34
	v_readlane_b32 s14, v254, 35
	v_readlane_b32 s15, v254, 36
	v_readlane_b32 s16, v254, 37
	s_waitcnt lgkmcnt(0)
	v_fma_f32 v85, v56, v76, -v34
	v_fma_f32 v84, v57, v77, -v35
	ds_read2st64_b32 v[34:35], v106 offset0:6 offset1:7
	v_readlane_b32 s17, v254, 38
	v_readlane_b32 s18, v254, 39
	v_readlane_b32 s19, v254, 40
	v_readlane_b32 s22, v254, 43
	s_waitcnt lgkmcnt(0)
	v_fma_f32 v58, v58, v78, -v34
	v_fma_f32 v57, v59, v79, -v35
	ds_read2st64_b32 v[34:35], v106 offset0:8 offset1:9
	v_readlane_b32 s23, v254, 44
	s_waitcnt lgkmcnt(0)
	v_fma_f32 v56, v60, v72, -v34
	v_fma_f32 v55, v61, v73, -v35
	ds_read2st64_b32 v[34:35], v106 offset0:10 offset1:11
	ds_read2st64_b32 v[60:61], v106 offset0:14 offset1:15
	s_waitcnt lgkmcnt(0)
	v_fma_f32 v54, v62, v74, -v34
	v_fma_f32 v53, v63, v75, -v35
	ds_read2st64_b32 v[34:35], v106 offset0:12 offset1:13
	v_fma_f32 v1, v67, v71, -v61
	s_waitcnt lgkmcnt(0)
	v_fma_f32 v52, v64, v68, -v34
	v_fma_f32 v34, v66, v70, -v60
	ds_read2st64_b32 v[60:61], v106 offset0:16 offset1:17
	v_fma_f32 v35, v65, v69, -v35
	s_waitcnt lgkmcnt(0)
	v_fma_f32 v66, v36, v80, -v60
	v_fma_f32 v65, v37, v81, -v61
	ds_read2st64_b32 v[36:37], v106 offset0:18 offset1:19
	v_mul_f32_e32 v107, v66, v66
	v_fmac_f32_e32 v107, v89, v89
	v_mul_f32_e32 v104, v65, v65
	v_fmac_f32_e32 v104, v88, v88
	s_waitcnt lgkmcnt(0)
	v_fma_f32 v64, v38, v82, -v36
	v_fma_f32 v63, v39, v83, -v37
	ds_read2st64_b32 v[36:37], v106 offset0:20 offset1:21
	v_mul_f32_e32 v103, v64, v64
	v_fmac_f32_e32 v103, v87, v87
	v_mul_f32_e32 v102, v63, v63
	v_fmac_f32_e32 v102, v86, v86
	s_waitcnt lgkmcnt(0)
	v_fma_f32 v61, v40, v76, -v36
	v_fma_f32 v59, v41, v77, -v37
	ds_read2st64_b32 v[36:37], v106 offset0:22 offset1:23
	v_mul_f32_e32 v101, v61, v61
	v_fmac_f32_e32 v101, v85, v85
	v_mul_f32_e32 v99, v59, v59
	v_fmac_f32_e32 v99, v84, v84
	s_waitcnt lgkmcnt(0)
	v_fma_f32 v62, v42, v78, -v36
	v_fma_f32 v60, v43, v79, -v37
	ds_read2st64_b32 v[36:37], v106 offset0:24 offset1:25
	v_mul_f32_e32 v100, v62, v62
	v_fmac_f32_e32 v100, v58, v58
	v_mul_f32_e32 v96, v60, v60
	v_fmac_f32_e32 v96, v57, v57
	s_waitcnt lgkmcnt(0)
	v_fma_f32 v43, v44, v72, -v36
	v_fma_f32 v42, v45, v73, -v37
	ds_read2st64_b32 v[36:37], v106 offset0:26 offset1:27
	ds_read2st64_b32 v[44:45], v106 offset0:30 offset1:31
	v_mul_f32_e32 v95, v43, v43
	v_fmac_f32_e32 v95, v56, v56
	v_mul_f32_e32 v90, v42, v42
	s_waitcnt lgkmcnt(0)
	v_fma_f32 v41, v46, v74, -v36
	v_fma_f32 v40, v47, v75, -v37
	ds_read2st64_b32 v[36:37], v106 offset0:28 offset1:29
	v_fma_f32 v39, v50, v70, -v44
	v_fmac_f32_e32 v90, v55, v55
	v_mul_f32_e32 v92, v41, v41
	v_fmac_f32_e32 v92, v54, v54
	s_waitcnt lgkmcnt(0)
	v_fma_f32 v38, v48, v68, -v36
	v_fma_f32 v36, v49, v69, -v37
	v_fma_f32 v37, v51, v71, -v45
	ds_read2st64_b32 v[44:45], v106 offset0:32 offset1:33
	v_mul_f32_e32 v91, v40, v40
	v_fmac_f32_e32 v91, v53, v53
	v_mul_f32_e32 v94, v38, v38
	v_fmac_f32_e32 v94, v52, v52
	s_waitcnt lgkmcnt(0)
	v_fma_f32 v51, v18, v80, -v44
	v_fma_f32 v50, v19, v81, -v45
	ds_read2st64_b32 v[18:19], v106 offset0:34 offset1:35
	v_fmac_f32_e32 v107, v51, v51
	v_fmac_f32_e32 v104, v50, v50
	v_mul_f32_e32 v93, v36, v36
	v_fmac_f32_e32 v93, v35, v35
	s_waitcnt lgkmcnt(0)
	v_fma_f32 v49, v20, v82, -v18
	v_fma_f32 v48, v21, v83, -v19
	ds_read2st64_b32 v[18:19], v106 offset0:36 offset1:37
	v_fmac_f32_e32 v103, v49, v49
	v_fmac_f32_e32 v102, v48, v48
	v_mul_f32_e32 v98, v39, v39
	v_fmac_f32_e32 v98, v34, v34
	s_waitcnt lgkmcnt(0)
	v_fma_f32 v47, v22, v76, -v18
	v_fma_f32 v45, v23, v77, -v19
	ds_read2st64_b32 v[18:19], v106 offset0:38 offset1:39
	v_fmac_f32_e32 v101, v47, v47
	v_fmac_f32_e32 v99, v45, v45
	v_mul_f32_e32 v97, v37, v37
	v_fmac_f32_e32 v97, v1, v1
	s_waitcnt lgkmcnt(0)
	v_fma_f32 v46, v24, v78, -v18
	v_fma_f32 v44, v25, v79, -v19
	ds_read2st64_b32 v[18:19], v106 offset0:40 offset1:41
	v_fmac_f32_e32 v100, v46, v46
	v_fmac_f32_e32 v96, v44, v44
	s_waitcnt lgkmcnt(0)
	v_fma_f32 v25, v26, v72, -v18
	v_fma_f32 v24, v27, v73, -v19
	ds_read2st64_b32 v[18:19], v106 offset0:42 offset1:43
	ds_read2st64_b32 v[26:27], v106 offset0:46 offset1:47
	v_fmac_f32_e32 v95, v25, v25
	v_fmac_f32_e32 v90, v24, v24
	s_waitcnt lgkmcnt(0)
	v_fma_f32 v23, v28, v74, -v18
	v_fma_f32 v22, v29, v75, -v19
	ds_read2st64_b32 v[18:19], v106 offset0:44 offset1:45
	v_fma_f32 v20, v32, v70, -v26
	v_fmac_f32_e32 v92, v23, v23
	v_fmac_f32_e32 v91, v22, v22
	v_fmac_f32_e32 v98, v20, v20
	s_waitcnt lgkmcnt(0)
	v_fma_f32 v21, v30, v68, -v18
	v_fma_f32 v18, v33, v71, -v27
	ds_read2st64_b32 v[26:27], v106 offset0:48 offset1:49
	v_fma_f32 v19, v31, v69, -v19
	v_fmac_f32_e32 v94, v21, v21
	v_fmac_f32_e32 v93, v19, v19
	v_fmac_f32_e32 v97, v18, v18
	s_waitcnt lgkmcnt(0)
	v_fma_f32 v67, v2, v80, -v26
	v_fma_f32 v33, v3, v81, -v27
	ds_read2st64_b32 v[2:3], v106 offset0:50 offset1:51
	v_fmac_f32_e32 v107, v67, v67
	v_fmac_f32_e32 v104, v33, v33
	s_waitcnt lgkmcnt(0)
; __device__ __forceinline__ void diff_unit(const Params& P, int l, int b, int h, int qb, float lam, float lam_init, LAS unsigned char* lds, bool dry = false) {
;     ...
;             for (int r = 0; r < 16; ++r) { const float v = o[d][r] * il[r] - xch[((wq * 4 + d) * 16 + r) * 64 + lane]; o[d][r] = v; ssq[r] += v * v; }
; #pragma unroll
;         for (int r = 0; r < 16; ++r) {
; #pragma unroll
;             for (int s = 1; s < 32; s <<= 1) ssq[r] += __shfl_xor(ssq[r], s);
	v_fma_f32 v32, v4, v82, -v2
	v_fma_f32 v31, v5, v83, -v3
	ds_read2st64_b32 v[2:3], v106 offset0:52 offset1:53
	v_fmac_f32_e32 v103, v32, v32
	v_fmac_f32_e32 v102, v31, v31
	s_waitcnt lgkmcnt(0)
	v_fma_f32 v30, v6, v76, -v2
	v_fma_f32 v28, v7, v77, -v3
	ds_read2st64_b32 v[2:3], v106 offset0:54 offset1:55
	v_fmac_f32_e32 v101, v30, v30
	v_fmac_f32_e32 v99, v28, v28
	v_or_b32_e32 v76, s64, v167
	v_mov_b32_e32 v77, v0
	s_waitcnt lgkmcnt(0)
	v_fma_f32 v29, v8, v78, -v2
	v_fma_f32 v27, v9, v79, -v3
	ds_read2st64_b32 v[2:3], v106 offset0:56 offset1:57
	v_fmac_f32_e32 v100, v29, v29
	v_fmac_f32_e32 v96, v27, v27
	v_lshl_add_u64 v[80:81], v[76:77], 2, s[20:21]
	s_waitcnt lgkmcnt(0)
	v_fma_f32 v26, v10, v72, -v2
	v_fma_f32 v10, v11, v73, -v3
	ds_read2st64_b32 v[2:3], v106 offset0:58 offset1:59
	v_fmac_f32_e32 v95, v26, v26
	v_fmac_f32_e32 v90, v10, v10
	s_waitcnt lgkmcnt(0)
	v_fma_f32 v9, v12, v74, -v2
	v_fma_f32 v8, v13, v75, -v3
	ds_read2st64_b32 v[2:3], v106 offset0:60 offset1:61
	v_fmac_f32_e32 v92, v9, v9
	v_fmac_f32_e32 v91, v8, v8
	s_waitcnt lgkmcnt(0)
	v_fma_f32 v7, v14, v68, -v2
	ds_read_b32 v2, v106 offset:15872
	v_fma_f32 v6, v15, v69, -v3
	v_fmac_f32_e32 v94, v7, v7
	v_fmac_f32_e32 v93, v6, v6
	s_waitcnt lgkmcnt(0)
	v_fma_f32 v5, v16, v70, -v2
	v_add_u32_e32 v2, s2, v105
	ds_read_b32 v2, v2
	v_fmac_f32_e32 v98, v5, v5
	s_lshl_b64 s[2:3], s[50:51], 10
	s_add_u32 s2, s90, s2
	s_addc_u32 s3, s91, s3
	s_waitcnt lgkmcnt(0)
	v_fma_f32 v4, v17, v71, -v2
	v_fmac_f32_e32 v97, v4, v4
	s_nop 1
	v_add_f32_dpp v107, v107, v107 quad_perm:[1,0,3,2] row_mask:0xf bank_mask:0xf
	v_add_f32_dpp v104, v104, v104 quad_perm:[1,0,3,2] row_mask:0xf bank_mask:0xf
	v_add_f32_dpp v103, v103, v103 quad_perm:[1,0,3,2] row_mask:0xf bank_mask:0xf
	v_add_f32_dpp v102, v102, v102 quad_perm:[1,0,3,2] row_mask:0xf bank_mask:0xf
	v_add_f32_dpp v101, v101, v101 quad_perm:[1,0,3,2] row_mask:0xf bank_mask:0xf
	v_add_f32_dpp v99, v99, v99 quad_perm:[1,0,3,2] row_mask:0xf bank_mask:0xf
	v_add_f32_dpp v100, v100, v100 quad_perm:[1,0,3,2] row_mask:0xf bank_mask:0xf
	v_add_f32_dpp v96, v96, v96 quad_perm:[1,0,3,2] row_mask:0xf bank_mask:0xf
	v_add_f32_dpp v95, v95, v95 quad_perm:[1,0,3,2] row_mask:0xf bank_mask:0xf
	v_add_f32_dpp v90, v90, v90 quad_perm:[1,0,3,2] row_mask:0xf bank_mask:0xf
	v_add_f32_dpp v92, v92, v92 quad_perm:[1,0,3,2] row_mask:0xf bank_mask:0xf
	v_add_f32_dpp v91, v91, v91 quad_perm:[1,0,3,2] row_mask:0xf bank_mask:0xf
	v_add_f32_dpp v94, v94, v94 quad_perm:[1,0,3,2] row_mask:0xf bank_mask:0xf
	v_add_f32_dpp v93, v93, v93 quad_perm:[1,0,3,2] row_mask:0xf bank_mask:0xf
	v_add_f32_dpp v98, v98, v98 quad_perm:[1,0,3,2] row_mask:0xf bank_mask:0xf
	v_add_f32_dpp v97, v97, v97 quad_perm:[1,0,3,2] row_mask:0xf bank_mask:0xf
	v_add_f32_dpp v107, v107, v107 quad_perm:[2,3,0,1] row_mask:0xf bank_mask:0xf
	v_add_f32_dpp v104, v104, v104 quad_perm:[2,3,0,1] row_mask:0xf bank_mask:0xf
	v_add_f32_dpp v103, v103, v103 quad_perm:[2,3,0,1] row_mask:0xf bank_mask:0xf
	v_add_f32_dpp v102, v102, v102 quad_perm:[2,3,0,1] row_mask:0xf bank_mask:0xf
	v_add_f32_dpp v101, v101, v101 quad_perm:[2,3,0,1] row_mask:0xf bank_mask:0xf
	v_add_f32_dpp v99, v99, v99 quad_perm:[2,3,0,1] row_mask:0xf bank_mask:0xf
	v_add_f32_dpp v100, v100, v100 quad_perm:[2,3,0,1] row_mask:0xf bank_mask:0xf
	v_add_f32_dpp v96, v96, v96 quad_perm:[2,3,0,1] row_mask:0xf bank_mask:0xf
	v_add_f32_dpp v95, v95, v95 quad_perm:[2,3,0,1] row_mask:0xf bank_mask:0xf
	v_add_f32_dpp v90, v90, v90 quad_perm:[2,3,0,1] row_mask:0xf bank_mask:0xf
	v_add_f32_dpp v92, v92, v92 quad_perm:[2,3,0,1] row_mask:0xf bank_mask:0xf
	v_add_f32_dpp v91, v91, v91 quad_perm:[2,3,0,1] row_mask:0xf bank_mask:0xf
	v_add_f32_dpp v94, v94, v94 quad_perm:[2,3,0,1] row_mask:0xf bank_mask:0xf
	v_add_f32_dpp v93, v93, v93 quad_perm:[2,3,0,1] row_mask:0xf bank_mask:0xf
	v_add_f32_dpp v98, v98, v98 quad_perm:[2,3,0,1] row_mask:0xf bank_mask:0xf
	v_add_f32_dpp v97, v97, v97 quad_perm:[2,3,0,1] row_mask:0xf bank_mask:0xf
	v_add_f32_dpp v107, v107, v107 row_half_mirror row_mask:0xf bank_mask:0xf
	v_add_f32_dpp v104, v104, v104 row_half_mirror row_mask:0xf bank_mask:0xf
	v_add_f32_dpp v103, v103, v103 row_half_mirror row_mask:0xf bank_mask:0xf
	v_add_f32_dpp v102, v102, v102 row_half_mirror row_mask:0xf bank_mask:0xf
	v_add_f32_dpp v101, v101, v101 row_half_mirror row_mask:0xf bank_mask:0xf
	v_add_f32_dpp v99, v99, v99 row_half_mirror row_mask:0xf bank_mask:0xf
	v_add_f32_dpp v100, v100, v100 row_half_mirror row_mask:0xf bank_mask:0xf
	v_add_f32_dpp v96, v96, v96 row_half_mirror row_mask:0xf bank_mask:0xf
	v_add_f32_dpp v95, v95, v95 row_half_mirror row_mask:0xf bank_mask:0xf
	v_add_f32_dpp v90, v90, v90 row_half_mirror row_mask:0xf bank_mask:0xf
	v_add_f32_dpp v92, v92, v92 row_half_mirror row_mask:0xf bank_mask:0xf
	v_add_f32_dpp v91, v91, v91 row_half_mirror row_mask:0xf bank_mask:0xf
	v_add_f32_dpp v94, v94, v94 row_half_mirror row_mask:0xf bank_mask:0xf
	v_add_f32_dpp v93, v93, v93 row_half_mirror row_mask:0xf bank_mask:0xf
	v_add_f32_dpp v98, v98, v98 row_half_mirror row_mask:0xf bank_mask:0xf
	v_add_f32_dpp v97, v97, v97 row_half_mirror row_mask:0xf bank_mask:0xf
	v_add_f32_dpp v107, v107, v107 row_mirror row_mask:0xf bank_mask:0xf
	v_add_f32_dpp v104, v104, v104 row_mirror row_mask:0xf bank_mask:0xf
	v_add_f32_dpp v103, v103, v103 row_mirror row_mask:0xf bank_mask:0xf
	v_add_f32_dpp v102, v102, v102 row_mirror row_mask:0xf bank_mask:0xf
	v_add_f32_dpp v101, v101, v101 row_mirror row_mask:0xf bank_mask:0xf
	v_add_f32_dpp v99, v99, v99 row_mirror row_mask:0xf bank_mask:0xf
	v_add_f32_dpp v100, v100, v100 row_mirror row_mask:0xf bank_mask:0xf
	v_add_f32_dpp v96, v96, v96 row_mirror row_mask:0xf bank_mask:0xf
	v_add_f32_dpp v95, v95, v95 row_mirror row_mask:0xf bank_mask:0xf
	v_add_f32_dpp v90, v90, v90 row_mirror row_mask:0xf bank_mask:0xf
	v_add_f32_dpp v92, v92, v92 row_mirror row_mask:0xf bank_mask:0xf
	v_add_f32_dpp v91, v91, v91 row_mirror row_mask:0xf bank_mask:0xf
	v_add_f32_dpp v94, v94, v94 row_mirror row_mask:0xf bank_mask:0xf
	v_add_f32_dpp v93, v93, v93 row_mirror row_mask:0xf bank_mask:0xf
	v_add_f32_dpp v98, v98, v98 row_mirror row_mask:0xf bank_mask:0xf
	v_add_f32_dpp v97, v97, v97 row_mirror row_mask:0xf bank_mask:0xf
	ds_bpermute_b32 v11, v253, v107
	s_waitcnt lgkmcnt(0)
; __device__ __forceinline__ unsigned f2bf(float f) { unsigned u = __builtin_bit_cast(unsigned, f); return (u + 0x7fffu + ((u >> 16) & 1u)) >> 16; }
; __device__ __forceinline__ float fast_rsq(float x) { return __builtin_amdgcn_rsqf(x); }
; __device__ __forceinline__ int crow(int r, int hi) { return (r & 3) + 8 * (r >> 2) + 4 * hi; }
; __device__ __forceinline__ void diff_unit(const Params& P, int l, int b, int h, int qb, float lam, float lam_init, LAS unsigned char* lds, bool dry = false) {
;     ...
;         for (int r = 0; r < 16; ++r) {
; #pragma unroll
;             for (int s = 1; s < 32; s <<= 1) ssq[r] += __shfl_xor(ssq[r], s);
;         }
;         const float post = 1.0f - lam_init;
;         float gsub[4];
; #pragma unroll
;         for (int d = 0; d < 4; ++d) gsub[d] = P.in[I_SUBG][l * 128 + 32 * d + r32] * post;
;         bf16_t* Ow = proj + O_DQ + (rowb + q0 + wq * 32) * QP + h * 128;
; #pragma unroll
;         for (int r = 0; r < 16; ++r) { const int q = crow(r, hi); const float rstd = fast_rsq(ssq[r] * (1.0f / 128.0f) + EPS);
; #pragma unroll
;             for (int d = 0; d < 4; ++d) if (!dry || o[d][r] == 1.2345e30f) Ow[(size_t)q * QP + 32 * d + r32] = (bf16_t)f2bf(o[d][r] * rstd * gsub[d]); }
	v_add_f32_e32 v107, v107, v11
	ds_bpermute_b32 v11, v253, v104
	s_waitcnt lgkmcnt(0)
	v_add_f32_e32 v104, v104, v11
	ds_bpermute_b32 v11, v253, v103
	s_waitcnt lgkmcnt(0)
	v_add_f32_e32 v103, v103, v11
	ds_bpermute_b32 v11, v253, v102
	s_waitcnt lgkmcnt(0)
	v_add_f32_e32 v102, v102, v11
	ds_bpermute_b32 v11, v253, v101
	s_waitcnt lgkmcnt(0)
	v_add_f32_e32 v101, v101, v11
	ds_bpermute_b32 v11, v253, v99
	s_waitcnt lgkmcnt(0)
	v_add_f32_e32 v99, v99, v11
	ds_bpermute_b32 v11, v253, v100
	s_waitcnt lgkmcnt(0)
	v_add_f32_e32 v100, v100, v11
	ds_bpermute_b32 v11, v253, v96
	s_waitcnt lgkmcnt(0)
	v_add_f32_e32 v96, v96, v11
	ds_bpermute_b32 v11, v253, v95
	s_waitcnt lgkmcnt(0)
	v_add_f32_e32 v95, v95, v11
	ds_bpermute_b32 v11, v253, v90
	s_waitcnt lgkmcnt(0)
	v_add_f32_e32 v90, v90, v11
	ds_bpermute_b32 v11, v253, v92
	s_waitcnt lgkmcnt(0)
	v_add_f32_e32 v92, v92, v11
	ds_bpermute_b32 v11, v253, v91
	s_waitcnt lgkmcnt(0)
	v_add_f32_e32 v91, v91, v11
	ds_bpermute_b32 v11, v253, v94
	s_waitcnt lgkmcnt(0)
	v_add_f32_e32 v94, v94, v11
	ds_bpermute_b32 v11, v253, v93
	s_waitcnt lgkmcnt(0)
	v_add_f32_e32 v93, v93, v11
	ds_bpermute_b32 v11, v253, v98
	s_waitcnt lgkmcnt(0)
	v_add_f32_e32 v98, v98, v11
	ds_bpermute_b32 v11, v253, v97
	s_waitcnt lgkmcnt(0)
	v_add_f32_e32 v97, v97, v11
	s_lshl_b32 s6, s82, 1
	s_add_u32 s2, s2, s6
	s_addc_u32 s3, s3, 0
	s_waitcnt lgkmcnt(0)
	v_mov_b32_e32 v2, v107
	v_fmamk_f32 v2, v2, 0x3c000000, v216
	v_rsq_f32_e32 v82, v2
	v_lshlrev_b32_e32 v2, 12, v166
	s_waitcnt lgkmcnt(0)
	v_mul_f32_e32 v66, v66, v82
	v_mul_f32_e32 v51, v51, v82
	s_waitcnt lgkmcnt(0)
	v_mov_b32_e32 v15, v104
	v_fmamk_f32 v15, v15, 0x3c000000, v216
	v_rsq_f32_e32 v15, v15
	s_waitcnt lgkmcnt(0)
	v_mul_f32_e32 v50, v50, v15
	s_waitcnt lgkmcnt(0)
	v_mov_b32_e32 v16, v103
	s_waitcnt lgkmcnt(0)
	v_mov_b32_e32 v68, v102
	s_waitcnt lgkmcnt(0)
	v_mov_b32_e32 v69, v101
	s_waitcnt lgkmcnt(0)
	v_mov_b32_e32 v70, v99
	s_waitcnt lgkmcnt(0)
	v_mov_b32_e32 v72, v100
	s_waitcnt lgkmcnt(0)
	v_mov_b32_e32 v73, v96
	s_waitcnt lgkmcnt(0)
	v_mov_b32_e32 v75, v95
	s_waitcnt lgkmcnt(0)
	v_mov_b32_e32 v74, v90
	s_waitcnt lgkmcnt(0)
	v_mov_b32_e32 v71, v92
	s_waitcnt lgkmcnt(0)
	v_mov_b32_e32 v17, v91
	s_waitcnt lgkmcnt(0)
	v_mov_b32_e32 v14, v94
	s_waitcnt lgkmcnt(0)
	v_mov_b32_e32 v13, v93
	s_waitcnt lgkmcnt(0)
	v_mov_b32_e32 v12, v98
	s_waitcnt lgkmcnt(0)
	v_mov_b32_e32 v11, v97
	global_load_dword v3, v[80:81], off
	s_waitcnt vmcnt(0)
	v_mul_f32_e32 v76, v194, v3
	global_load_dword v3, v[80:81], off offset:128
	s_waitcnt vmcnt(0)
	v_mul_f32_e32 v77, v194, v3
	global_load_dword v3, v[80:81], off offset:256
	v_mul_f32_e32 v66, v66, v77
	s_waitcnt vmcnt(0)
	v_mul_f32_e32 v78, v194, v3
	global_load_dword v3, v[80:81], off offset:384
	v_lshlrev_b32_e32 v80, 1, v167
	v_mov_b32_e32 v81, v0
	v_lshl_add_u64 v[80:81], s[2:3], 0, v[80:81]
	v_mul_f32_e32 v51, v51, v78
	s_movk_i32 s2, 0x4000
	v_mul_f32_e32 v50, v50, v78
	s_waitcnt vmcnt(0)
	v_mul_f32_e32 v79, v194, v3
	v_mov_b32_e32 v3, v0
	v_lshl_add_u64 v[2:3], v[80:81], 0, v[2:3]
	v_mul_f32_e32 v80, v89, v82
	v_mul_f32_e32 v80, v80, v76
	v_bfe_u32 v81, v80, 16, 1
	v_add3_u32 v80, v80, v81, s60
	global_store_short_d16_hi v[2:3], v80, off
	v_bfe_u32 v80, v66, 16, 1
	v_add3_u32 v66, v66, v80, s60
	global_store_short_d16_hi v[2:3], v66, off offset:64
	v_bfe_u32 v66, v51, 16, 1
	v_add3_u32 v51, v51, v66, s60
	global_store_short_d16_hi v[2:3], v51, off offset:128
	v_mul_f32_e32 v51, v67, v82
	v_mul_f32_e32 v51, v51, v79
	v_bfe_u32 v66, v51, 16, 1
	v_add3_u32 v51, v51, v66, s60
	global_store_short_d16_hi v[2:3], v51, off offset:192
	v_mul_f32_e32 v51, v88, v15
	v_mul_f32_e32 v51, v51, v76
	v_bfe_u32 v66, v51, 16, 1
	v_add3_u32 v51, v51, v66, s60
	global_store_short_d16_hi v[2:3], v51, off offset:1024
	v_mul_f32_e32 v51, v65, v15
	v_mul_f32_e32 v15, v33, v15
	v_mul_f32_e32 v15, v15, v79
	v_bfe_u32 v33, v15, 16, 1
	v_add3_u32 v15, v15, v33, s60
	global_store_short_d16_hi v[2:3], v15, off offset:1216
	v_fmamk_f32 v15, v16, 0x3c000000, v216
	v_rsq_f32_e32 v15, v15
	v_mul_f32_e32 v51, v51, v77
	v_bfe_u32 v65, v51, 16, 1
	v_add3_u32 v51, v51, v65, s60
	v_mul_f32_e32 v16, v87, v15
	v_mul_f32_e32 v16, v16, v76
	v_bfe_u32 v33, v16, 16, 1
	v_add3_u32 v16, v16, v33, s60
	global_store_short_d16_hi v[2:3], v16, off offset:2048
	v_mul_f32_e32 v16, v64, v15
	v_mul_f32_e32 v16, v16, v77
	v_bfe_u32 v33, v16, 16, 1
	v_add3_u32 v16, v16, v33, s60
	global_store_short_d16_hi v[2:3], v16, off offset:2112
	v_mul_f32_e32 v16, v49, v15
	v_mul_f32_e32 v16, v16, v78
	v_bfe_u32 v33, v16, 16, 1
	v_mul_f32_e32 v15, v32, v15
	v_add3_u32 v16, v16, v33, s60
	v_mul_f32_e32 v15, v15, v79
	global_store_short_d16_hi v[2:3], v16, off offset:2176
	v_bfe_u32 v16, v15, 16, 1
	v_add3_u32 v15, v15, v16, s60
	global_store_short_d16_hi v[2:3], v15, off offset:2240
	v_fmamk_f32 v15, v68, 0x3c000000, v216
	v_rsq_f32_e32 v15, v15
	global_store_short_d16_hi v[2:3], v51, off offset:1088
	v_bfe_u32 v51, v50, 16, 1
	v_add3_u32 v50, v50, v51, s60
	v_mul_f32_e32 v16, v86, v15
	v_mul_f32_e32 v16, v16, v76
	v_bfe_u32 v32, v16, 16, 1
	v_add3_u32 v16, v16, v32, s60
	global_store_short_d16_hi v[2:3], v16, off offset:3072
	v_mul_f32_e32 v16, v63, v15
	v_mul_f32_e32 v16, v16, v77
	v_bfe_u32 v32, v16, 16, 1
	v_add3_u32 v16, v16, v32, s60
	global_store_short_d16_hi v[2:3], v16, off offset:3136
	v_mul_f32_e32 v16, v48, v15
	v_mul_f32_e32 v16, v16, v78
	v_bfe_u32 v32, v16, 16, 1
	v_mul_f32_e32 v15, v31, v15
	v_add3_u32 v16, v16, v32, s60
	v_mul_f32_e32 v15, v15, v79
	global_store_short_d16_hi v[2:3], v16, off offset:3200
	v_bfe_u32 v16, v15, 16, 1
	v_add3_u32 v15, v15, v16, s60
; __device__ __forceinline__ unsigned f2bf(float f) { unsigned u = __builtin_bit_cast(unsigned, f); return (u + 0x7fffu + ((u >> 16) & 1u)) >> 16; }
; __device__ __forceinline__ float fast_rsq(float x) { return __builtin_amdgcn_rsqf(x); }
; __device__ __forceinline__ int crow(int r, int hi) { return (r & 3) + 8 * (r >> 2) + 4 * hi; }
; __device__ __forceinline__ void diff_unit(const Params& P, int l, int b, int h, int qb, float lam, float lam_init, LAS unsigned char* lds, bool dry = false) {
;     ...
;         for (int d = 0; d < 4; ++d) gsub[d] = P.in[I_SUBG][l * 128 + 32 * d + r32] * post;
;         bf16_t* Ow = proj + O_DQ + (rowb + q0 + wq * 32) * QP + h * 128;
; #pragma unroll
;         for (int r = 0; r < 16; ++r) { const int q = crow(r, hi); const float rstd = fast_rsq(ssq[r] * (1.0f / 128.0f) + EPS);
; #pragma unroll
;             for (int d = 0; d < 4; ++d) if (!dry || o[d][r] == 1.2345e30f) Ow[(size_t)q * QP + 32 * d + r32] = (bf16_t)f2bf(o[d][r] * rstd * gsub[d]); }
	global_store_short_d16_hi v[2:3], v15, off offset:3264
	v_fmamk_f32 v15, v69, 0x3c000000, v216
	v_rsq_f32_e32 v15, v15
	v_add_co_u32_e32 v32, vcc, s77, v2
	global_store_short_d16_hi v[2:3], v50, off offset:1152
	v_mul_f32_e32 v16, v85, v15
	v_mul_f32_e32 v16, v16, v76
	v_bfe_u32 v31, v16, 16, 1
	v_add3_u32 v16, v16, v31, s60
	v_addc_co_u32_e32 v33, vcc, 0, v3, vcc
	global_store_short_d16_hi v[32:33], v16, off
	v_mul_f32_e32 v16, v61, v15
	v_mul_f32_e32 v16, v16, v77
	v_bfe_u32 v31, v16, 16, 1
	v_add3_u32 v16, v16, v31, s60
	global_store_short_d16_hi v[32:33], v16, off offset:64
	v_mul_f32_e32 v16, v47, v15
	v_mul_f32_e32 v16, v16, v78
	v_bfe_u32 v31, v16, 16, 1
	v_mul_f32_e32 v15, v30, v15
	v_add3_u32 v16, v16, v31, s60
	v_mul_f32_e32 v15, v15, v79
	global_store_short_d16_hi v[32:33], v16, off offset:128
	v_bfe_u32 v16, v15, 16, 1
	v_add3_u32 v15, v15, v16, s60
	global_store_short_d16_hi v[32:33], v15, off offset:192
	v_fmamk_f32 v15, v70, 0x3c000000, v216
	v_rsq_f32_e32 v15, v15
	s_nop 0
	v_mul_f32_e32 v16, v84, v15
	v_mul_f32_e32 v16, v16, v76
	v_bfe_u32 v30, v16, 16, 1
	v_add3_u32 v16, v16, v30, s60
	global_store_short_d16_hi v[32:33], v16, off offset:1024
	v_mul_f32_e32 v16, v59, v15
	v_mul_f32_e32 v16, v16, v77
	v_bfe_u32 v30, v16, 16, 1
	v_add3_u32 v16, v16, v30, s60
	global_store_short_d16_hi v[32:33], v16, off offset:1088
	v_mul_f32_e32 v16, v45, v15
	v_mul_f32_e32 v16, v16, v78
	v_bfe_u32 v30, v16, 16, 1
	v_mul_f32_e32 v15, v28, v15
	v_add3_u32 v16, v16, v30, s60
	v_mul_f32_e32 v15, v15, v79
	global_store_short_d16_hi v[32:33], v16, off offset:1152
	v_bfe_u32 v16, v15, 16, 1
	v_add3_u32 v15, v15, v16, s60
	global_store_short_d16_hi v[32:33], v15, off offset:1216
	v_fmamk_f32 v15, v72, 0x3c000000, v216
	v_rsq_f32_e32 v15, v15
	s_nop 0
	v_mul_f32_e32 v16, v58, v15
	v_mul_f32_e32 v16, v16, v76
	v_bfe_u32 v28, v16, 16, 1
	v_add3_u32 v16, v16, v28, s60
	global_store_short_d16_hi v[32:33], v16, off offset:2048
	v_mul_f32_e32 v16, v62, v15
	v_mul_f32_e32 v16, v16, v77
	v_bfe_u32 v28, v16, 16, 1
	v_add3_u32 v16, v16, v28, s60
	global_store_short_d16_hi v[32:33], v16, off offset:2112
	v_mul_f32_e32 v16, v46, v15
	v_mul_f32_e32 v16, v16, v78
	v_bfe_u32 v28, v16, 16, 1
	v_mul_f32_e32 v15, v29, v15
	v_add3_u32 v16, v16, v28, s60
	v_mul_f32_e32 v15, v15, v79
	global_store_short_d16_hi v[32:33], v16, off offset:2176
	v_bfe_u32 v16, v15, 16, 1
	v_add3_u32 v15, v15, v16, s60
	global_store_short_d16_hi v[32:33], v15, off offset:2240
	v_fmamk_f32 v15, v73, 0x3c000000, v216
	v_rsq_f32_e32 v15, v15
	s_nop 0
	v_mul_f32_e32 v16, v57, v15
	v_mul_f32_e32 v16, v16, v76
	v_bfe_u32 v28, v16, 16, 1
	v_add3_u32 v16, v16, v28, s60
	global_store_short_d16_hi v[32:33], v16, off offset:3072
	v_mul_f32_e32 v16, v60, v15
	v_mul_f32_e32 v16, v16, v77
	v_bfe_u32 v28, v16, 16, 1
	v_add3_u32 v16, v16, v28, s60
	global_store_short_d16_hi v[32:33], v16, off offset:3136
	v_mul_f32_e32 v16, v44, v15
	v_mul_f32_e32 v16, v16, v78
	v_bfe_u32 v28, v16, 16, 1
	v_mul_f32_e32 v15, v27, v15
	v_add3_u32 v16, v16, v28, s60
	v_mul_f32_e32 v15, v15, v79
	global_store_short_d16_hi v[32:33], v16, off offset:3200
	v_bfe_u32 v16, v15, 16, 1
	v_add3_u32 v15, v15, v16, s60
	global_store_short_d16_hi v[32:33], v15, off offset:3264
	v_fmamk_f32 v15, v75, 0x3c000000, v216
	v_rsq_f32_e32 v15, v15
	v_add_co_u32_e32 v28, vcc, s2, v2
	s_movk_i32 s2, 0x6000
	v_mul_f32_e32 v16, v56, v15
	v_mul_f32_e32 v16, v16, v76
	v_bfe_u32 v27, v16, 16, 1
	v_add3_u32 v16, v16, v27, s60
	v_addc_co_u32_e32 v29, vcc, 0, v3, vcc
	global_store_short_d16_hi v[28:29], v16, off
	v_mul_f32_e32 v16, v43, v15
	v_mul_f32_e32 v16, v16, v77
	v_bfe_u32 v27, v16, 16, 1
	v_add3_u32 v16, v16, v27, s60
	global_store_short_d16_hi v[28:29], v16, off offset:64
	v_mul_f32_e32 v16, v25, v15
	v_mul_f32_e32 v16, v16, v78
	v_bfe_u32 v25, v16, 16, 1
	v_mul_f32_e32 v15, v26, v15
	v_add3_u32 v16, v16, v25, s60
	v_mul_f32_e32 v15, v15, v79
	global_store_short_d16_hi v[28:29], v16, off offset:128
	v_bfe_u32 v16, v15, 16, 1
	v_add3_u32 v15, v15, v16, s60
	global_store_short_d16_hi v[28:29], v15, off offset:192
	v_fmamk_f32 v15, v74, 0x3c000000, v216
	v_rsq_f32_e32 v15, v15
	v_add_co_u32_e32 v2, vcc, s2, v2
	v_mul_f32_e32 v16, v55, v15
	v_mul_f32_e32 v16, v16, v76
	v_bfe_u32 v25, v16, 16, 1
	v_add3_u32 v16, v16, v25, s60
	global_store_short_d16_hi v[28:29], v16, off offset:1024
	v_mul_f32_e32 v16, v42, v15
	v_mul_f32_e32 v16, v16, v77
	v_bfe_u32 v25, v16, 16, 1
	v_mul_f32_e32 v10, v10, v15
	v_add3_u32 v16, v16, v25, s60
	v_mul_f32_e32 v10, v10, v79
	global_store_short_d16_hi v[28:29], v16, off offset:1088
	v_mul_f32_e32 v16, v24, v15
; __device__ __forceinline__ unsigned f2bf(float f) { unsigned u = __builtin_bit_cast(unsigned, f); return (u + 0x7fffu + ((u >> 16) & 1u)) >> 16; }
; __device__ __forceinline__ float fast_rsq(float x) { return __builtin_amdgcn_rsqf(x); }
; __device__ __forceinline__ int crow(int r, int hi) { return (r & 3) + 8 * (r >> 2) + 4 * hi; }
; __device__ __forceinline__ void diff_unit(const Params& P, int l, int b, int h, int qb, float lam, float lam_init, LAS unsigned char* lds, bool dry = false) {
;     ...
;         for (int r = 0; r < 16; ++r) { const int q = crow(r, hi); const float rstd = fast_rsq(ssq[r] * (1.0f / 128.0f) + EPS);
; #pragma unroll
;             for (int d = 0; d < 4; ++d) if (!dry || o[d][r] == 1.2345e30f) Ow[(size_t)q * QP + 32 * d + r32] = (bf16_t)f2bf(o[d][r] * rstd * gsub[d]); }
	v_bfe_u32 v15, v10, 16, 1
	v_add3_u32 v10, v10, v15, s60
	global_store_short_d16_hi v[28:29], v10, off offset:1216
	v_fmamk_f32 v10, v71, 0x3c000000, v216
	v_rsq_f32_e32 v10, v10
	v_mul_f32_e32 v16, v16, v78
	v_bfe_u32 v24, v16, 16, 1
	v_add3_u32 v16, v16, v24, s60
	v_mul_f32_e32 v15, v54, v10
	v_mul_f32_e32 v15, v15, v76
	global_store_short_d16_hi v[28:29], v16, off offset:1152
	v_bfe_u32 v16, v15, 16, 1
	v_add3_u32 v15, v15, v16, s60
	global_store_short_d16_hi v[28:29], v15, off offset:2048
	v_mul_f32_e32 v15, v41, v10
	v_mul_f32_e32 v15, v15, v77
	v_bfe_u32 v16, v15, 16, 1
	v_mul_f32_e32 v9, v9, v10
	v_add3_u32 v15, v15, v16, s60
	v_mul_f32_e32 v9, v9, v79
	global_store_short_d16_hi v[28:29], v15, off offset:2112
	v_mul_f32_e32 v15, v23, v10
	v_bfe_u32 v10, v9, 16, 1
	v_add3_u32 v9, v9, v10, s60
	global_store_short_d16_hi v[28:29], v9, off offset:2240
	v_fmamk_f32 v9, v17, 0x3c000000, v216
	v_rsq_f32_e32 v9, v9
	v_mul_f32_e32 v15, v15, v78
	v_bfe_u32 v16, v15, 16, 1
	v_add3_u32 v15, v15, v16, s60
	v_mul_f32_e32 v10, v53, v9
	v_mul_f32_e32 v10, v10, v76
	global_store_short_d16_hi v[28:29], v15, off offset:2176
	v_bfe_u32 v15, v10, 16, 1
	v_add3_u32 v10, v10, v15, s60
	global_store_short_d16_hi v[28:29], v10, off offset:3072
	v_mul_f32_e32 v10, v40, v9
	v_mul_f32_e32 v10, v10, v77
	v_bfe_u32 v15, v10, 16, 1
	v_mul_f32_e32 v8, v8, v9
	v_add3_u32 v10, v10, v15, s60
	v_mul_f32_e32 v8, v8, v79
	global_store_short_d16_hi v[28:29], v10, off offset:3136
	v_mul_f32_e32 v10, v22, v9
	v_bfe_u32 v9, v8, 16, 1
	v_add3_u32 v8, v8, v9, s60
	global_store_short_d16_hi v[28:29], v8, off offset:3264
	v_fmamk_f32 v8, v14, 0x3c000000, v216
	v_rsq_f32_e32 v8, v8
	v_mul_f32_e32 v10, v10, v78
	v_bfe_u32 v15, v10, 16, 1
	v_add3_u32 v10, v10, v15, s60
	v_mul_f32_e32 v9, v52, v8
	v_mul_f32_e32 v9, v9, v76
	global_store_short_d16_hi v[28:29], v10, off offset:3200
	v_bfe_u32 v10, v9, 16, 1
	v_add3_u32 v9, v9, v10, s60
	v_addc_co_u32_e32 v3, vcc, 0, v3, vcc
	global_store_short_d16_hi v[2:3], v9, off
	v_mul_f32_e32 v9, v38, v8
	v_mul_f32_e32 v9, v9, v77
	v_bfe_u32 v10, v9, 16, 1
	v_mul_f32_e32 v7, v7, v8
	v_add3_u32 v9, v9, v10, s60
	v_mul_f32_e32 v7, v7, v79
	global_store_short_d16_hi v[2:3], v9, off offset:64
	v_mul_f32_e32 v9, v21, v8
	v_bfe_u32 v8, v7, 16, 1
	v_add3_u32 v7, v7, v8, s60
	global_store_short_d16_hi v[2:3], v7, off offset:192
	v_fmamk_f32 v7, v13, 0x3c000000, v216
	v_rsq_f32_e32 v7, v7
	v_mul_f32_e32 v9, v9, v78
	v_bfe_u32 v10, v9, 16, 1
	v_add3_u32 v9, v9, v10, s60
	v_mul_f32_e32 v8, v35, v7
	v_mul_f32_e32 v8, v8, v76
	global_store_short_d16_hi v[2:3], v9, off offset:128
	v_bfe_u32 v9, v8, 16, 1
	v_add3_u32 v8, v8, v9, s60
	global_store_short_d16_hi v[2:3], v8, off offset:1024
	v_mul_f32_e32 v8, v36, v7
	v_mul_f32_e32 v8, v8, v77
	v_bfe_u32 v9, v8, 16, 1
	v_mul_f32_e32 v6, v6, v7
	v_add3_u32 v8, v8, v9, s60
	v_mul_f32_e32 v6, v6, v79
	global_store_short_d16_hi v[2:3], v8, off offset:1088
	v_mul_f32_e32 v8, v19, v7
	v_bfe_u32 v7, v6, 16, 1
	v_add3_u32 v6, v6, v7, s60
	global_store_short_d16_hi v[2:3], v6, off offset:1216
	v_fmamk_f32 v6, v12, 0x3c000000, v216
	v_rsq_f32_e32 v6, v6
	v_mul_f32_e32 v8, v8, v78
	v_bfe_u32 v9, v8, 16, 1
	v_add3_u32 v8, v8, v9, s60
	v_mul_f32_e32 v7, v34, v6
	v_mul_f32_e32 v7, v7, v76
	global_store_short_d16_hi v[2:3], v8, off offset:1152
	v_bfe_u32 v8, v7, 16, 1
	v_add3_u32 v7, v7, v8, s60
	global_store_short_d16_hi v[2:3], v7, off offset:2048
	v_mul_f32_e32 v7, v39, v6
	v_mul_f32_e32 v7, v7, v77
	v_bfe_u32 v8, v7, 16, 1
	v_mul_f32_e32 v5, v5, v6
	v_add3_u32 v7, v7, v8, s60
	v_mul_f32_e32 v5, v5, v79
	global_store_short_d16_hi v[2:3], v7, off offset:2112
	v_mul_f32_e32 v7, v20, v6
	v_bfe_u32 v6, v5, 16, 1
	v_add3_u32 v5, v5, v6, s60
	global_store_short_d16_hi v[2:3], v5, off offset:2240
	v_fmamk_f32 v5, v11, 0x3c000000, v216
	v_rsq_f32_e32 v5, v5
	v_mul_f32_e32 v7, v7, v78
	v_bfe_u32 v8, v7, 16, 1
	v_add3_u32 v7, v7, v8, s60
	v_mul_f32_e32 v1, v1, v5
	v_mul_f32_e32 v1, v76, v1
	v_bfe_u32 v6, v1, 16, 1
	v_add3_u32 v1, v1, v6, s60
	global_store_short_d16_hi v[2:3], v1, off offset:3072
	v_mul_f32_e32 v1, v37, v5
	v_mul_f32_e32 v1, v77, v1
	v_bfe_u32 v6, v1, 16, 1
	v_add3_u32 v1, v1, v6, s60
	global_store_short_d16_hi v[2:3], v1, off offset:3136
	v_mul_f32_e32 v1, v18, v5
	v_mul_f32_e32 v1, v78, v1
	v_bfe_u32 v6, v1, 16, 1
	v_add3_u32 v1, v1, v6, s60
	global_store_short_d16_hi v[2:3], v1, off offset:3200
	v_mul_f32_e32 v1, v4, v5
	v_mul_f32_e32 v1, v79, v1
	v_bfe_u32 v4, v1, 16, 1
	v_add3_u32 v1, v1, v4, s60
	global_store_short_d16_hi v[2:3], v7, off offset:2176
	global_store_short_d16_hi v[2:3], v1, off offset:3264

; __device__ __forceinline__ void diff_unit(const Params& P, int l, int b, int h, int qb, float lam, float lam_init, LAS unsigned char* lds, bool dry = false) {
;     ...
;         for (int d = 0; d < 4; ++d)
; #pragma unroll
;             for (int r = 0; r < 16; ++r) { const float v = o[d][r] * il[r] - xch[((wq * 4 + d) * 16 + r) * 64 + lane]; o[d][r] = v; ssq[r] += v * v; }
.LBB0_563:
	s_cmpk_gt_u32 s52, 0xff
	s_waitcnt lgkmcnt(0)
	s_barrier
	s_cbranch_scc1 .LBB0_389
	s_add_i32 s2, 0, 0x13800
	v_lshl_add_u32 v105, v189, 2, s2
	s_lshl_b32 s2, s52, 8
	s_and_b32 s3, s2, 0xc000
	v_add_u32_e32 v106, s3, v105
	ds_read2st64_b32 v[82:83], v106 offset1:1
	s_or_b32 s2, s2, 0x3f00
	v_readlane_b32 s4, v254, 29
	v_readlane_b32 s16, v254, 41
	v_readlane_b32 s17, v254, 42
	s_waitcnt lgkmcnt(0)
	v_fma_f32 v89, v50, v78, -v82
	v_fma_f32 v88, v51, v79, -v83
	ds_read2st64_b32 v[50:51], v106 offset0:2 offset1:3
	v_readlane_b32 s5, v254, 30
	v_readlane_b32 s6, v254, 31
	v_readlane_b32 s7, v254, 32
	v_readlane_b32 s8, v254, 33
	s_waitcnt lgkmcnt(0)
	v_fma_f32 v87, v52, v80, -v50
	v_fma_f32 v86, v53, v81, -v51
	ds_read2st64_b32 v[50:51], v106 offset0:4 offset1:5
	v_readlane_b32 s9, v254, 34
	v_readlane_b32 s10, v254, 35
	v_readlane_b32 s11, v254, 36
	v_readlane_b32 s12, v254, 37
	s_waitcnt lgkmcnt(0)
	v_fma_f32 v85, v54, v74, -v50
	v_fma_f32 v84, v55, v75, -v51
	ds_read2st64_b32 v[50:51], v106 offset0:6 offset1:7
	v_readlane_b32 s13, v254, 38
	v_readlane_b32 s14, v254, 39
	v_readlane_b32 s15, v254, 40
	v_readlane_b32 s18, v254, 43
	s_waitcnt lgkmcnt(0)
	v_fma_f32 v83, v56, v76, -v50
	v_fma_f32 v82, v57, v77, -v51
	ds_read2st64_b32 v[50:51], v106 offset0:8 offset1:9
	v_readlane_b32 s19, v254, 44
	s_waitcnt lgkmcnt(0)
	v_fma_f32 v57, v58, v70, -v50
	v_fma_f32 v56, v59, v71, -v51
	ds_read2st64_b32 v[50:51], v106 offset0:10 offset1:11
	ds_read2st64_b32 v[58:59], v106 offset0:14 offset1:15
	s_waitcnt lgkmcnt(0)
	v_fma_f32 v55, v60, v72, -v50
	v_fma_f32 v54, v61, v73, -v51
	ds_read2st64_b32 v[50:51], v106 offset0:12 offset1:13
	s_waitcnt lgkmcnt(0)
	v_fma_f32 v53, v62, v66, -v50
	v_fma_f32 v52, v63, v67, -v51
	v_fma_f32 v51, v64, v68, -v58
	v_fma_f32 v50, v65, v69, -v59
	ds_read2st64_b32 v[58:59], v106 offset0:16 offset1:17
	s_waitcnt lgkmcnt(0)
	v_fma_f32 v65, v34, v78, -v58
	v_fma_f32 v64, v35, v79, -v59
	ds_read2st64_b32 v[34:35], v106 offset0:18 offset1:19
	v_mul_f32_e32 v107, v65, v65
	v_fmac_f32_e32 v107, v89, v89
	v_mul_f32_e32 v104, v64, v64
	v_fmac_f32_e32 v104, v88, v88
	s_waitcnt lgkmcnt(0)
	v_fma_f32 v63, v36, v80, -v34
	v_fma_f32 v62, v37, v81, -v35
	ds_read2st64_b32 v[34:35], v106 offset0:20 offset1:21
	v_mul_f32_e32 v103, v63, v63
	v_fmac_f32_e32 v103, v87, v87
	v_mul_f32_e32 v102, v62, v62
	v_fmac_f32_e32 v102, v86, v86
	s_waitcnt lgkmcnt(0)
	v_fma_f32 v60, v38, v74, -v34
	v_fma_f32 v58, v39, v75, -v35
	ds_read2st64_b32 v[34:35], v106 offset0:22 offset1:23
	v_mul_f32_e32 v101, v60, v60
	v_fmac_f32_e32 v101, v85, v85
	v_mul_f32_e32 v99, v58, v58
	v_fmac_f32_e32 v99, v84, v84
	s_waitcnt lgkmcnt(0)
	v_fma_f32 v61, v40, v76, -v34
	v_fma_f32 v59, v41, v77, -v35
	ds_read2st64_b32 v[34:35], v106 offset0:24 offset1:25
	v_mul_f32_e32 v100, v61, v61
	v_fmac_f32_e32 v100, v83, v83
	v_mul_f32_e32 v96, v59, v59
	v_fmac_f32_e32 v96, v82, v82
	s_waitcnt lgkmcnt(0)
	v_fma_f32 v41, v42, v70, -v34
	v_fma_f32 v40, v43, v71, -v35
	ds_read2st64_b32 v[34:35], v106 offset0:26 offset1:27
	ds_read2st64_b32 v[42:43], v106 offset0:30 offset1:31
	v_mul_f32_e32 v95, v41, v41
	v_fmac_f32_e32 v95, v57, v57
	v_mul_f32_e32 v90, v40, v40
	s_waitcnt lgkmcnt(0)
	v_fma_f32 v39, v44, v72, -v34
	v_fma_f32 v38, v45, v73, -v35
	ds_read2st64_b32 v[34:35], v106 offset0:28 offset1:29
	v_fma_f32 v37, v48, v68, -v42
	v_fmac_f32_e32 v90, v56, v56
	v_mul_f32_e32 v92, v39, v39
	v_fmac_f32_e32 v92, v55, v55
	s_waitcnt lgkmcnt(0)
	v_fma_f32 v36, v46, v66, -v34
	v_fma_f32 v34, v47, v67, -v35
	v_fma_f32 v35, v49, v69, -v43
	ds_read2st64_b32 v[42:43], v106 offset0:32 offset1:33
	v_mul_f32_e32 v91, v38, v38
	v_fmac_f32_e32 v91, v54, v54
	v_mul_f32_e32 v94, v36, v36
	v_fmac_f32_e32 v94, v53, v53
	s_waitcnt lgkmcnt(0)
	v_fma_f32 v49, v18, v78, -v42
	v_fma_f32 v48, v19, v79, -v43
	ds_read2st64_b32 v[18:19], v106 offset0:34 offset1:35
	v_fmac_f32_e32 v107, v49, v49
	v_fmac_f32_e32 v104, v48, v48
	v_mul_f32_e32 v93, v34, v34
	v_fmac_f32_e32 v93, v52, v52
	s_waitcnt lgkmcnt(0)
	v_fma_f32 v47, v20, v80, -v18
	v_fma_f32 v46, v21, v81, -v19
	ds_read2st64_b32 v[18:19], v106 offset0:36 offset1:37
	v_fmac_f32_e32 v103, v47, v47
	v_fmac_f32_e32 v102, v46, v46
	v_mul_f32_e32 v98, v37, v37
	v_fmac_f32_e32 v98, v51, v51
	s_waitcnt lgkmcnt(0)
	v_fma_f32 v45, v22, v74, -v18
	v_fma_f32 v43, v23, v75, -v19
	ds_read2st64_b32 v[18:19], v106 offset0:38 offset1:39
	v_fmac_f32_e32 v101, v45, v45
	v_fmac_f32_e32 v99, v43, v43
	v_mul_f32_e32 v97, v35, v35
	v_fmac_f32_e32 v97, v50, v50
	s_waitcnt lgkmcnt(0)
	v_fma_f32 v44, v24, v76, -v18
	v_fma_f32 v42, v25, v77, -v19
	ds_read2st64_b32 v[18:19], v106 offset0:40 offset1:41
	v_fmac_f32_e32 v100, v44, v44
	v_fmac_f32_e32 v96, v42, v42
	s_waitcnt lgkmcnt(0)
	v_fma_f32 v25, v26, v70, -v18
	v_fma_f32 v24, v27, v71, -v19
	ds_read2st64_b32 v[18:19], v106 offset0:42 offset1:43
	ds_read2st64_b32 v[26:27], v106 offset0:46 offset1:47
	v_fmac_f32_e32 v95, v25, v25
	v_fmac_f32_e32 v90, v24, v24
	s_waitcnt lgkmcnt(0)
	v_fma_f32 v23, v28, v72, -v18
	v_fma_f32 v22, v29, v73, -v19
	ds_read2st64_b32 v[18:19], v106 offset0:44 offset1:45
	v_fma_f32 v20, v32, v68, -v26
	v_fmac_f32_e32 v92, v23, v23
	v_fmac_f32_e32 v91, v22, v22
	v_fmac_f32_e32 v98, v20, v20
	s_waitcnt lgkmcnt(0)
	v_fma_f32 v21, v30, v66, -v18
	v_fma_f32 v18, v33, v69, -v27
	ds_read2st64_b32 v[26:27], v106 offset0:48 offset1:49
	v_fma_f32 v19, v31, v67, -v19
	v_fmac_f32_e32 v94, v21, v21
	v_fmac_f32_e32 v93, v19, v19
	v_fmac_f32_e32 v97, v18, v18
	s_waitcnt lgkmcnt(0)
	v_fma_f32 v78, v2, v78, -v26
	v_fma_f32 v33, v3, v79, -v27
	ds_read2st64_b32 v[2:3], v106 offset0:50 offset1:51
	v_fmac_f32_e32 v107, v78, v78
	v_fmac_f32_e32 v104, v33, v33
	s_waitcnt lgkmcnt(0)
; __device__ __forceinline__ void diff_unit(const Params& P, int l, int b, int h, int qb, float lam, float lam_init, LAS unsigned char* lds, bool dry = false) {
;     ...
;             for (int r = 0; r < 16; ++r) { const float v = o[d][r] * il[r] - xch[((wq * 4 + d) * 16 + r) * 64 + lane]; o[d][r] = v; ssq[r] += v * v; }
; #pragma unroll
;         for (int r = 0; r < 16; ++r) {
; #pragma unroll
;             for (int s = 1; s < 32; s <<= 1) ssq[r] += __shfl_xor(ssq[r], s);
	v_fma_f32 v32, v4, v80, -v2
	v_fma_f32 v31, v5, v81, -v3
	ds_read2st64_b32 v[2:3], v106 offset0:52 offset1:53
	v_fmac_f32_e32 v103, v32, v32
	v_fmac_f32_e32 v102, v31, v31
	s_waitcnt lgkmcnt(0)
	v_fma_f32 v30, v6, v74, -v2
	v_fma_f32 v28, v7, v75, -v3
	ds_read2st64_b32 v[2:3], v106 offset0:54 offset1:55
	v_fmac_f32_e32 v101, v30, v30
	v_fmac_f32_e32 v99, v28, v28
	v_or_b32_e32 v74, s64, v186
	v_mov_b32_e32 v75, v0
	s_waitcnt lgkmcnt(0)
	v_fma_f32 v29, v8, v76, -v2
	v_fma_f32 v27, v9, v77, -v3
	ds_read2st64_b32 v[2:3], v106 offset0:56 offset1:57
	v_fmac_f32_e32 v100, v29, v29
	v_fmac_f32_e32 v96, v27, v27
	v_lshl_add_u64 v[80:81], v[74:75], 2, s[16:17]
	s_waitcnt lgkmcnt(0)
	v_fma_f32 v26, v10, v70, -v2
	v_fma_f32 v10, v11, v71, -v3
	ds_read2st64_b32 v[2:3], v106 offset0:58 offset1:59
	v_fmac_f32_e32 v95, v26, v26
	v_fmac_f32_e32 v90, v10, v10
	s_waitcnt lgkmcnt(0)
	v_fma_f32 v9, v12, v72, -v2
	v_fma_f32 v8, v13, v73, -v3
	ds_read2st64_b32 v[2:3], v106 offset0:60 offset1:61
	v_fmac_f32_e32 v92, v9, v9
	v_fmac_f32_e32 v91, v8, v8
	s_waitcnt lgkmcnt(0)
	v_fma_f32 v7, v14, v66, -v2
	ds_read_b32 v2, v106 offset:15872
	v_fma_f32 v6, v15, v67, -v3
	v_fmac_f32_e32 v94, v7, v7
	v_fmac_f32_e32 v93, v6, v6
	s_waitcnt lgkmcnt(0)
	v_fma_f32 v5, v16, v68, -v2
	v_add_u32_e32 v2, s2, v105
	ds_read_b32 v2, v2
	v_fmac_f32_e32 v98, v5, v5
	s_lshl_b64 s[2:3], s[90:91], 10
	s_add_u32 s2, s50, s2
	s_addc_u32 s3, s51, s3
	s_waitcnt lgkmcnt(0)
	v_fma_f32 v4, v17, v69, -v2
	v_fmac_f32_e32 v97, v4, v4
	s_nop 1
	v_add_f32_dpp v107, v107, v107 quad_perm:[1,0,3,2] row_mask:0xf bank_mask:0xf
	v_add_f32_dpp v104, v104, v104 quad_perm:[1,0,3,2] row_mask:0xf bank_mask:0xf
	v_add_f32_dpp v103, v103, v103 quad_perm:[1,0,3,2] row_mask:0xf bank_mask:0xf
	v_add_f32_dpp v102, v102, v102 quad_perm:[1,0,3,2] row_mask:0xf bank_mask:0xf
	v_add_f32_dpp v101, v101, v101 quad_perm:[1,0,3,2] row_mask:0xf bank_mask:0xf
	v_add_f32_dpp v99, v99, v99 quad_perm:[1,0,3,2] row_mask:0xf bank_mask:0xf
	v_add_f32_dpp v100, v100, v100 quad_perm:[1,0,3,2] row_mask:0xf bank_mask:0xf
	v_add_f32_dpp v96, v96, v96 quad_perm:[1,0,3,2] row_mask:0xf bank_mask:0xf
	v_add_f32_dpp v95, v95, v95 quad_perm:[1,0,3,2] row_mask:0xf bank_mask:0xf
	v_add_f32_dpp v90, v90, v90 quad_perm:[1,0,3,2] row_mask:0xf bank_mask:0xf
	v_add_f32_dpp v92, v92, v92 quad_perm:[1,0,3,2] row_mask:0xf bank_mask:0xf
	v_add_f32_dpp v91, v91, v91 quad_perm:[1,0,3,2] row_mask:0xf bank_mask:0xf
	v_add_f32_dpp v94, v94, v94 quad_perm:[1,0,3,2] row_mask:0xf bank_mask:0xf
	v_add_f32_dpp v93, v93, v93 quad_perm:[1,0,3,2] row_mask:0xf bank_mask:0xf
	v_add_f32_dpp v98, v98, v98 quad_perm:[1,0,3,2] row_mask:0xf bank_mask:0xf
	v_add_f32_dpp v97, v97, v97 quad_perm:[1,0,3,2] row_mask:0xf bank_mask:0xf
	v_add_f32_dpp v107, v107, v107 quad_perm:[2,3,0,1] row_mask:0xf bank_mask:0xf
	v_add_f32_dpp v104, v104, v104 quad_perm:[2,3,0,1] row_mask:0xf bank_mask:0xf
	v_add_f32_dpp v103, v103, v103 quad_perm:[2,3,0,1] row_mask:0xf bank_mask:0xf
	v_add_f32_dpp v102, v102, v102 quad_perm:[2,3,0,1] row_mask:0xf bank_mask:0xf
	v_add_f32_dpp v101, v101, v101 quad_perm:[2,3,0,1] row_mask:0xf bank_mask:0xf
	v_add_f32_dpp v99, v99, v99 quad_perm:[2,3,0,1] row_mask:0xf bank_mask:0xf
	v_add_f32_dpp v100, v100, v100 quad_perm:[2,3,0,1] row_mask:0xf bank_mask:0xf
	v_add_f32_dpp v96, v96, v96 quad_perm:[2,3,0,1] row_mask:0xf bank_mask:0xf
	v_add_f32_dpp v95, v95, v95 quad_perm:[2,3,0,1] row_mask:0xf bank_mask:0xf
	v_add_f32_dpp v90, v90, v90 quad_perm:[2,3,0,1] row_mask:0xf bank_mask:0xf
	v_add_f32_dpp v92, v92, v92 quad_perm:[2,3,0,1] row_mask:0xf bank_mask:0xf
	v_add_f32_dpp v91, v91, v91 quad_perm:[2,3,0,1] row_mask:0xf bank_mask:0xf
	v_add_f32_dpp v94, v94, v94 quad_perm:[2,3,0,1] row_mask:0xf bank_mask:0xf
	v_add_f32_dpp v93, v93, v93 quad_perm:[2,3,0,1] row_mask:0xf bank_mask:0xf
	v_add_f32_dpp v98, v98, v98 quad_perm:[2,3,0,1] row_mask:0xf bank_mask:0xf
	v_add_f32_dpp v97, v97, v97 quad_perm:[2,3,0,1] row_mask:0xf bank_mask:0xf
	v_add_f32_dpp v107, v107, v107 row_half_mirror row_mask:0xf bank_mask:0xf
	v_add_f32_dpp v104, v104, v104 row_half_mirror row_mask:0xf bank_mask:0xf
	v_add_f32_dpp v103, v103, v103 row_half_mirror row_mask:0xf bank_mask:0xf
	v_add_f32_dpp v102, v102, v102 row_half_mirror row_mask:0xf bank_mask:0xf
	v_add_f32_dpp v101, v101, v101 row_half_mirror row_mask:0xf bank_mask:0xf
	v_add_f32_dpp v99, v99, v99 row_half_mirror row_mask:0xf bank_mask:0xf
	v_add_f32_dpp v100, v100, v100 row_half_mirror row_mask:0xf bank_mask:0xf
	v_add_f32_dpp v96, v96, v96 row_half_mirror row_mask:0xf bank_mask:0xf
	v_add_f32_dpp v95, v95, v95 row_half_mirror row_mask:0xf bank_mask:0xf
	v_add_f32_dpp v90, v90, v90 row_half_mirror row_mask:0xf bank_mask:0xf
	v_add_f32_dpp v92, v92, v92 row_half_mirror row_mask:0xf bank_mask:0xf
	v_add_f32_dpp v91, v91, v91 row_half_mirror row_mask:0xf bank_mask:0xf
	v_add_f32_dpp v94, v94, v94 row_half_mirror row_mask:0xf bank_mask:0xf
	v_add_f32_dpp v93, v93, v93 row_half_mirror row_mask:0xf bank_mask:0xf
	v_add_f32_dpp v98, v98, v98 row_half_mirror row_mask:0xf bank_mask:0xf
	v_add_f32_dpp v97, v97, v97 row_half_mirror row_mask:0xf bank_mask:0xf
	v_add_f32_dpp v107, v107, v107 row_mirror row_mask:0xf bank_mask:0xf
	v_add_f32_dpp v104, v104, v104 row_mirror row_mask:0xf bank_mask:0xf
	v_add_f32_dpp v103, v103, v103 row_mirror row_mask:0xf bank_mask:0xf
	v_add_f32_dpp v102, v102, v102 row_mirror row_mask:0xf bank_mask:0xf
	v_add_f32_dpp v101, v101, v101 row_mirror row_mask:0xf bank_mask:0xf
	v_add_f32_dpp v99, v99, v99 row_mirror row_mask:0xf bank_mask:0xf
	v_add_f32_dpp v100, v100, v100 row_mirror row_mask:0xf bank_mask:0xf
	v_add_f32_dpp v96, v96, v96 row_mirror row_mask:0xf bank_mask:0xf
	v_add_f32_dpp v95, v95, v95 row_mirror row_mask:0xf bank_mask:0xf
	v_add_f32_dpp v90, v90, v90 row_mirror row_mask:0xf bank_mask:0xf
	v_add_f32_dpp v92, v92, v92 row_mirror row_mask:0xf bank_mask:0xf
	v_add_f32_dpp v91, v91, v91 row_mirror row_mask:0xf bank_mask:0xf
	v_add_f32_dpp v94, v94, v94 row_mirror row_mask:0xf bank_mask:0xf
	v_add_f32_dpp v93, v93, v93 row_mirror row_mask:0xf bank_mask:0xf
	v_add_f32_dpp v98, v98, v98 row_mirror row_mask:0xf bank_mask:0xf
	v_add_f32_dpp v97, v97, v97 row_mirror row_mask:0xf bank_mask:0xf
	ds_bpermute_b32 v11, v253, v107
	s_waitcnt lgkmcnt(0)
; __device__ __forceinline__ unsigned f2bf(float f) { unsigned u = __builtin_bit_cast(unsigned, f); return (u + 0x7fffu + ((u >> 16) & 1u)) >> 16; }
; __device__ __forceinline__ float fast_rsq(float x) { return __builtin_amdgcn_rsqf(x); }
; __device__ __forceinline__ int crow(int r, int hi) { return (r & 3) + 8 * (r >> 2) + 4 * hi; }
; __device__ __forceinline__ void diff_unit(const Params& P, int l, int b, int h, int qb, float lam, float lam_init, LAS unsigned char* lds, bool dry = false) {
;     ...
;         for (int r = 0; r < 16; ++r) {
; #pragma unroll
;             for (int s = 1; s < 32; s <<= 1) ssq[r] += __shfl_xor(ssq[r], s);
;         }
;         const float post = 1.0f - lam_init;
;         float gsub[4];
; #pragma unroll
;         for (int d = 0; d < 4; ++d) gsub[d] = P.in[I_SUBG][l * 128 + 32 * d + r32] * post;
;         bf16_t* Ow = proj + O_DQ + (rowb + q0 + wq * 32) * QP + h * 128;
; #pragma unroll
;         for (int r = 0; r < 16; ++r) { const int q = crow(r, hi); const float rstd = fast_rsq(ssq[r] * (1.0f / 128.0f) + EPS);
; #pragma unroll
;             for (int d = 0; d < 4; ++d) if (!dry || o[d][r] == 1.2345e30f) Ow[(size_t)q * QP + 32 * d + r32] = (bf16_t)f2bf(o[d][r] * rstd * gsub[d]); }
	v_add_f32_e32 v107, v107, v11
	ds_bpermute_b32 v11, v253, v104
	s_waitcnt lgkmcnt(0)
	v_add_f32_e32 v104, v104, v11
	ds_bpermute_b32 v11, v253, v103
	s_waitcnt lgkmcnt(0)
	v_add_f32_e32 v103, v103, v11
	ds_bpermute_b32 v11, v253, v102
	s_waitcnt lgkmcnt(0)
	v_add_f32_e32 v102, v102, v11
	ds_bpermute_b32 v11, v253, v101
	s_waitcnt lgkmcnt(0)
	v_add_f32_e32 v101, v101, v11
	ds_bpermute_b32 v11, v253, v99
	s_waitcnt lgkmcnt(0)
	v_add_f32_e32 v99, v99, v11
	ds_bpermute_b32 v11, v253, v100
	s_waitcnt lgkmcnt(0)
	v_add_f32_e32 v100, v100, v11
	ds_bpermute_b32 v11, v253, v96
	s_waitcnt lgkmcnt(0)
	v_add_f32_e32 v96, v96, v11
	ds_bpermute_b32 v11, v253, v95
	s_waitcnt lgkmcnt(0)
	v_add_f32_e32 v95, v95, v11
	ds_bpermute_b32 v11, v253, v90
	s_waitcnt lgkmcnt(0)
	v_add_f32_e32 v90, v90, v11
	ds_bpermute_b32 v11, v253, v92
	s_waitcnt lgkmcnt(0)
	v_add_f32_e32 v92, v92, v11
	ds_bpermute_b32 v11, v253, v91
	s_waitcnt lgkmcnt(0)
	v_add_f32_e32 v91, v91, v11
	ds_bpermute_b32 v11, v253, v94
	s_waitcnt lgkmcnt(0)
	v_add_f32_e32 v94, v94, v11
	ds_bpermute_b32 v11, v253, v93
	s_waitcnt lgkmcnt(0)
	v_add_f32_e32 v93, v93, v11
	ds_bpermute_b32 v11, v253, v98
	s_waitcnt lgkmcnt(0)
	v_add_f32_e32 v98, v98, v11
	ds_bpermute_b32 v11, v253, v97
	s_waitcnt lgkmcnt(0)
	v_add_f32_e32 v97, v97, v11
	s_add_u32 s2, s2, s96
	s_addc_u32 s3, s3, 0
	s_waitcnt lgkmcnt(0)
	v_mov_b32_e32 v2, v107
	v_fmamk_f32 v2, v2, 0x3c000000, v216
	v_rsq_f32_e32 v79, v2
	v_lshlrev_b32_e32 v2, 12, v1
	s_waitcnt lgkmcnt(0)
	v_mul_f32_e32 v1, v89, v79
	s_waitcnt lgkmcnt(0)
	v_mov_b32_e32 v15, v104
	s_waitcnt lgkmcnt(0)
	v_mov_b32_e32 v16, v103
	s_waitcnt lgkmcnt(0)
	v_mov_b32_e32 v66, v102
	s_waitcnt lgkmcnt(0)
	v_mov_b32_e32 v67, v101
	s_waitcnt lgkmcnt(0)
	v_mov_b32_e32 v68, v99
	s_waitcnt lgkmcnt(0)
	v_mov_b32_e32 v70, v100
	s_waitcnt lgkmcnt(0)
	v_mov_b32_e32 v71, v96
	s_waitcnt lgkmcnt(0)
	v_mov_b32_e32 v73, v95
	s_waitcnt lgkmcnt(0)
	v_mov_b32_e32 v72, v90
	s_waitcnt lgkmcnt(0)
	v_mov_b32_e32 v69, v92
	s_waitcnt lgkmcnt(0)
	v_mov_b32_e32 v17, v91
	s_waitcnt lgkmcnt(0)
	v_mov_b32_e32 v14, v94
	s_waitcnt lgkmcnt(0)
	v_mov_b32_e32 v13, v93
	s_waitcnt lgkmcnt(0)
	v_mov_b32_e32 v12, v98
	s_waitcnt lgkmcnt(0)
	v_mov_b32_e32 v11, v97
	global_load_dword v3, v[80:81], off
	s_waitcnt vmcnt(0)
	v_mul_f32_e32 v74, v194, v3
	global_load_dword v3, v[80:81], off offset:128
	v_mul_f32_e32 v1, v1, v74
	s_waitcnt vmcnt(0)
	v_mul_f32_e32 v75, v194, v3
	global_load_dword v3, v[80:81], off offset:256
	s_waitcnt vmcnt(0)
	v_mul_f32_e32 v76, v194, v3
	global_load_dword v3, v[80:81], off offset:384
	v_lshlrev_b32_e32 v80, 1, v186
	v_mov_b32_e32 v81, v0
	v_lshl_add_u64 v[80:81], s[2:3], 0, v[80:81]
	s_movk_i32 s2, 0x4000
	s_waitcnt vmcnt(0)
	v_mul_f32_e32 v77, v194, v3
	v_mov_b32_e32 v3, v0
	v_lshl_add_u64 v[2:3], v[80:81], 0, v[2:3]
	v_bfe_u32 v80, v1, 16, 1
	v_add3_u32 v1, v1, v80, s60
	global_store_short_d16_hi v[2:3], v1, off
	v_mul_f32_e32 v1, v65, v79
	v_mul_f32_e32 v1, v1, v75
	v_bfe_u32 v65, v1, 16, 1
	v_add3_u32 v1, v1, v65, s60
	global_store_short_d16_hi v[2:3], v1, off offset:64
	v_mul_f32_e32 v1, v49, v79
	v_mul_f32_e32 v1, v1, v76
	v_bfe_u32 v49, v1, 16, 1
	v_add3_u32 v1, v1, v49, s60
	global_store_short_d16_hi v[2:3], v1, off offset:128
	v_mul_f32_e32 v1, v78, v79
	v_mul_f32_e32 v1, v1, v77
	v_bfe_u32 v49, v1, 16, 1
	v_add3_u32 v1, v1, v49, s60
	global_store_short_d16_hi v[2:3], v1, off offset:192
	v_fmamk_f32 v1, v15, 0x3c000000, v216
	v_rsq_f32_e32 v1, v1
	s_nop 0
	v_mul_f32_e32 v15, v88, v1
	v_mul_f32_e32 v15, v15, v74
	v_bfe_u32 v49, v15, 16, 1
	v_add3_u32 v15, v15, v49, s60
	global_store_short_d16_hi v[2:3], v15, off offset:1024
	v_mul_f32_e32 v15, v64, v1
	v_mul_f32_e32 v15, v15, v75
	v_bfe_u32 v49, v15, 16, 1
	v_add3_u32 v15, v15, v49, s60
	global_store_short_d16_hi v[2:3], v15, off offset:1088
	v_mul_f32_e32 v15, v48, v1
	v_mul_f32_e32 v15, v15, v76
	v_bfe_u32 v48, v15, 16, 1
	v_mul_f32_e32 v1, v33, v1
	v_add3_u32 v15, v15, v48, s60
	v_mul_f32_e32 v1, v1, v77
	global_store_short_d16_hi v[2:3], v15, off offset:1152
	v_bfe_u32 v15, v1, 16, 1
	v_add3_u32 v1, v1, v15, s60
	global_store_short_d16_hi v[2:3], v1, off offset:1216
	v_fmamk_f32 v1, v16, 0x3c000000, v216
	v_rsq_f32_e32 v1, v1
	s_nop 0
	v_mul_f32_e32 v15, v87, v1
	v_mul_f32_e32 v15, v15, v74
	v_bfe_u32 v16, v15, 16, 1
	v_add3_u32 v15, v15, v16, s60
	global_store_short_d16_hi v[2:3], v15, off offset:2048
	v_mul_f32_e32 v15, v63, v1
	v_mul_f32_e32 v15, v15, v75
	v_bfe_u32 v16, v15, 16, 1
	v_add3_u32 v15, v15, v16, s60
	global_store_short_d16_hi v[2:3], v15, off offset:2112
	v_mul_f32_e32 v15, v47, v1
	v_mul_f32_e32 v15, v15, v76
	v_bfe_u32 v16, v15, 16, 1
	v_mul_f32_e32 v1, v32, v1
	v_add3_u32 v15, v15, v16, s60
	v_mul_f32_e32 v1, v1, v77
	global_store_short_d16_hi v[2:3], v15, off offset:2176
	v_bfe_u32 v15, v1, 16, 1
	v_add3_u32 v1, v1, v15, s60
	global_store_short_d16_hi v[2:3], v1, off offset:2240
	v_fmamk_f32 v1, v66, 0x3c000000, v216
	v_rsq_f32_e32 v1, v1
	v_add_co_u32_e32 v32, vcc, s77, v2
	v_mul_f32_e32 v15, v86, v1
	v_mul_f32_e32 v15, v15, v74
	v_bfe_u32 v16, v15, 16, 1
	v_add3_u32 v15, v15, v16, s60
	global_store_short_d16_hi v[2:3], v15, off offset:3072
	v_mul_f32_e32 v15, v62, v1
	v_mul_f32_e32 v15, v15, v75
	v_bfe_u32 v16, v15, 16, 1
	v_add3_u32 v15, v15, v16, s60
	global_store_short_d16_hi v[2:3], v15, off offset:3136
	v_mul_f32_e32 v15, v46, v1
	v_mul_f32_e32 v15, v15, v76
	v_bfe_u32 v16, v15, 16, 1
	v_mul_f32_e32 v1, v31, v1
	v_add3_u32 v15, v15, v16, s60
	v_mul_f32_e32 v1, v1, v77
	global_store_short_d16_hi v[2:3], v15, off offset:3200
	v_bfe_u32 v15, v1, 16, 1
	v_add3_u32 v1, v1, v15, s60
; __device__ __forceinline__ unsigned f2bf(float f) { unsigned u = __builtin_bit_cast(unsigned, f); return (u + 0x7fffu + ((u >> 16) & 1u)) >> 16; }
; __device__ __forceinline__ float fast_rsq(float x) { return __builtin_amdgcn_rsqf(x); }
; __device__ __forceinline__ int crow(int r, int hi) { return (r & 3) + 8 * (r >> 2) + 4 * hi; }
; __device__ __forceinline__ void diff_unit(const Params& P, int l, int b, int h, int qb, float lam, float lam_init, LAS unsigned char* lds, bool dry = false) {
;     ...
;         for (int r = 0; r < 16; ++r) { const int q = crow(r, hi); const float rstd = fast_rsq(ssq[r] * (1.0f / 128.0f) + EPS);
; #pragma unroll
;             for (int d = 0; d < 4; ++d) if (!dry || o[d][r] == 1.2345e30f) Ow[(size_t)q * QP + 32 * d + r32] = (bf16_t)f2bf(o[d][r] * rstd * gsub[d]); }
	global_store_short_d16_hi v[2:3], v1, off offset:3264
	v_fmamk_f32 v1, v67, 0x3c000000, v216
	v_rsq_f32_e32 v1, v1
	v_addc_co_u32_e32 v33, vcc, 0, v3, vcc
	v_mul_f32_e32 v15, v85, v1
	v_mul_f32_e32 v15, v15, v74
	v_bfe_u32 v16, v15, 16, 1
	v_add3_u32 v15, v15, v16, s60
	global_store_short_d16_hi v[32:33], v15, off
	v_mul_f32_e32 v15, v60, v1
	v_mul_f32_e32 v15, v15, v75
	v_bfe_u32 v16, v15, 16, 1
	v_add3_u32 v15, v15, v16, s60
	global_store_short_d16_hi v[32:33], v15, off offset:64
	v_mul_f32_e32 v15, v45, v1
	v_mul_f32_e32 v15, v15, v76
	v_bfe_u32 v16, v15, 16, 1
	v_mul_f32_e32 v1, v30, v1
	v_add3_u32 v15, v15, v16, s60
	v_mul_f32_e32 v1, v1, v77
	global_store_short_d16_hi v[32:33], v15, off offset:128
	v_bfe_u32 v15, v1, 16, 1
	v_add3_u32 v1, v1, v15, s60
	global_store_short_d16_hi v[32:33], v1, off offset:192
	v_fmamk_f32 v1, v68, 0x3c000000, v216
	v_rsq_f32_e32 v1, v1
	s_nop 0
	v_mul_f32_e32 v15, v84, v1
	v_mul_f32_e32 v15, v15, v74
	v_bfe_u32 v16, v15, 16, 1
	v_add3_u32 v15, v15, v16, s60
	global_store_short_d16_hi v[32:33], v15, off offset:1024
	v_mul_f32_e32 v15, v58, v1
	v_mul_f32_e32 v15, v15, v75
	v_bfe_u32 v16, v15, 16, 1
	v_add3_u32 v15, v15, v16, s60
	global_store_short_d16_hi v[32:33], v15, off offset:1088
	v_mul_f32_e32 v15, v43, v1
	v_mul_f32_e32 v15, v15, v76
	v_bfe_u32 v16, v15, 16, 1
	v_mul_f32_e32 v1, v28, v1
	v_add3_u32 v15, v15, v16, s60
	v_mul_f32_e32 v1, v1, v77
	global_store_short_d16_hi v[32:33], v15, off offset:1152
	v_bfe_u32 v15, v1, 16, 1
	v_add3_u32 v1, v1, v15, s60
	global_store_short_d16_hi v[32:33], v1, off offset:1216
	v_fmamk_f32 v1, v70, 0x3c000000, v216
	v_rsq_f32_e32 v1, v1
	v_add_co_u32_e32 v28, vcc, s2, v2
	s_movk_i32 s2, 0x6000
	v_mul_f32_e32 v15, v83, v1
	v_mul_f32_e32 v15, v15, v74
	v_bfe_u32 v16, v15, 16, 1
	v_add3_u32 v15, v15, v16, s60
	global_store_short_d16_hi v[32:33], v15, off offset:2048
	v_mul_f32_e32 v15, v61, v1
	v_mul_f32_e32 v15, v15, v75
	v_bfe_u32 v16, v15, 16, 1
	v_add3_u32 v15, v15, v16, s60
	global_store_short_d16_hi v[32:33], v15, off offset:2112
	v_mul_f32_e32 v15, v44, v1
	v_mul_f32_e32 v15, v15, v76
	v_bfe_u32 v16, v15, 16, 1
	v_mul_f32_e32 v1, v29, v1
	v_add3_u32 v15, v15, v16, s60
	v_mul_f32_e32 v1, v1, v77
	global_store_short_d16_hi v[32:33], v15, off offset:2176
	v_bfe_u32 v15, v1, 16, 1
	v_add3_u32 v1, v1, v15, s60
	global_store_short_d16_hi v[32:33], v1, off offset:2240
	v_fmamk_f32 v1, v71, 0x3c000000, v216
	v_rsq_f32_e32 v1, v1
	v_addc_co_u32_e32 v29, vcc, 0, v3, vcc
	v_add_co_u32_e32 v2, vcc, s2, v2
	v_mul_f32_e32 v15, v82, v1
	v_mul_f32_e32 v15, v15, v74
	v_bfe_u32 v16, v15, 16, 1
	v_add3_u32 v15, v15, v16, s60
	global_store_short_d16_hi v[32:33], v15, off offset:3072
	v_mul_f32_e32 v15, v59, v1
	v_mul_f32_e32 v15, v15, v75
	v_bfe_u32 v16, v15, 16, 1
	v_add3_u32 v15, v15, v16, s60
	global_store_short_d16_hi v[32:33], v15, off offset:3136
	v_mul_f32_e32 v15, v42, v1
	v_mul_f32_e32 v15, v15, v76
	v_bfe_u32 v16, v15, 16, 1
	v_mul_f32_e32 v1, v27, v1
	v_add3_u32 v15, v15, v16, s60
	v_mul_f32_e32 v1, v1, v77
	global_store_short_d16_hi v[32:33], v15, off offset:3200
	v_bfe_u32 v15, v1, 16, 1
	v_add3_u32 v1, v1, v15, s60
	global_store_short_d16_hi v[32:33], v1, off offset:3264
	v_fmamk_f32 v1, v73, 0x3c000000, v216
	v_rsq_f32_e32 v1, v1
	v_addc_co_u32_e32 v3, vcc, 0, v3, vcc
	v_mul_f32_e32 v15, v57, v1
	v_mul_f32_e32 v15, v15, v74
	v_bfe_u32 v16, v15, 16, 1
	v_add3_u32 v15, v15, v16, s60
	global_store_short_d16_hi v[28:29], v15, off
	v_mul_f32_e32 v15, v41, v1
	v_mul_f32_e32 v15, v15, v75
	v_bfe_u32 v16, v15, 16, 1
	v_add3_u32 v15, v15, v16, s60
	global_store_short_d16_hi v[28:29], v15, off offset:64
	v_mul_f32_e32 v15, v25, v1
	v_mul_f32_e32 v15, v15, v76
	v_bfe_u32 v16, v15, 16, 1
	v_mul_f32_e32 v1, v26, v1
	v_add3_u32 v15, v15, v16, s60
	v_mul_f32_e32 v1, v1, v77
	global_store_short_d16_hi v[28:29], v15, off offset:128
	v_bfe_u32 v15, v1, 16, 1
	v_add3_u32 v1, v1, v15, s60
	global_store_short_d16_hi v[28:29], v1, off offset:192
	v_fmamk_f32 v1, v72, 0x3c000000, v216
	v_rsq_f32_e32 v1, v1
	s_nop 0
	v_mul_f32_e32 v15, v56, v1
	v_mul_f32_e32 v15, v15, v74
	v_bfe_u32 v16, v15, 16, 1
	v_add3_u32 v15, v15, v16, s60
	global_store_short_d16_hi v[28:29], v15, off offset:1024
	v_mul_f32_e32 v15, v40, v1
	v_mul_f32_e32 v15, v15, v75
	v_bfe_u32 v16, v15, 16, 1
	v_add3_u32 v15, v15, v16, s60
	global_store_short_d16_hi v[28:29], v15, off offset:1088
	v_mul_f32_e32 v15, v24, v1
	v_mul_f32_e32 v1, v10, v1
	v_mul_f32_e32 v1, v1, v77
	v_bfe_u32 v10, v1, 16, 1
	v_add3_u32 v1, v1, v10, s60
; __device__ __forceinline__ unsigned f2bf(float f) { unsigned u = __builtin_bit_cast(unsigned, f); return (u + 0x7fffu + ((u >> 16) & 1u)) >> 16; }
; __device__ __forceinline__ float fast_rsq(float x) { return __builtin_amdgcn_rsqf(x); }
; __device__ __forceinline__ int crow(int r, int hi) { return (r & 3) + 8 * (r >> 2) + 4 * hi; }
; __device__ __forceinline__ void diff_unit(const Params& P, int l, int b, int h, int qb, float lam, float lam_init, LAS unsigned char* lds, bool dry = false) {
;     ...
;         for (int r = 0; r < 16; ++r) { const int q = crow(r, hi); const float rstd = fast_rsq(ssq[r] * (1.0f / 128.0f) + EPS);
; #pragma unroll
;             for (int d = 0; d < 4; ++d) if (!dry || o[d][r] == 1.2345e30f) Ow[(size_t)q * QP + 32 * d + r32] = (bf16_t)f2bf(o[d][r] * rstd * gsub[d]); }
	global_store_short_d16_hi v[28:29], v1, off offset:1216
	v_fmamk_f32 v1, v69, 0x3c000000, v216
	v_rsq_f32_e32 v1, v1
	v_mul_f32_e32 v15, v15, v76
	v_bfe_u32 v16, v15, 16, 1
	v_add3_u32 v15, v15, v16, s60
	v_mul_f32_e32 v10, v55, v1
	v_mul_f32_e32 v10, v10, v74
	global_store_short_d16_hi v[28:29], v15, off offset:1152
	v_bfe_u32 v15, v10, 16, 1
	v_add3_u32 v10, v10, v15, s60
	global_store_short_d16_hi v[28:29], v10, off offset:2048
	v_mul_f32_e32 v10, v39, v1
	v_mul_f32_e32 v10, v10, v75
	v_bfe_u32 v15, v10, 16, 1
	v_add3_u32 v10, v10, v15, s60
	global_store_short_d16_hi v[28:29], v10, off offset:2112
	v_mul_f32_e32 v10, v23, v1
	v_mul_f32_e32 v1, v9, v1
	v_mul_f32_e32 v1, v1, v77
	v_bfe_u32 v9, v1, 16, 1
	v_add3_u32 v1, v1, v9, s60
	global_store_short_d16_hi v[28:29], v1, off offset:2240
	v_fmamk_f32 v1, v17, 0x3c000000, v216
	v_rsq_f32_e32 v1, v1
	v_mul_f32_e32 v10, v10, v76
	v_bfe_u32 v15, v10, 16, 1
	v_add3_u32 v10, v10, v15, s60
	v_mul_f32_e32 v9, v54, v1
	v_mul_f32_e32 v9, v9, v74
	global_store_short_d16_hi v[28:29], v10, off offset:2176
	v_bfe_u32 v10, v9, 16, 1
	v_add3_u32 v9, v9, v10, s60
	global_store_short_d16_hi v[28:29], v9, off offset:3072
	v_mul_f32_e32 v9, v38, v1
	v_mul_f32_e32 v9, v9, v75
	v_bfe_u32 v10, v9, 16, 1
	v_add3_u32 v9, v9, v10, s60
	global_store_short_d16_hi v[28:29], v9, off offset:3136
	v_mul_f32_e32 v9, v22, v1
	v_mul_f32_e32 v1, v8, v1
	v_mul_f32_e32 v1, v1, v77
	v_bfe_u32 v8, v1, 16, 1
	v_add3_u32 v1, v1, v8, s60
	global_store_short_d16_hi v[28:29], v1, off offset:3264
	v_fmamk_f32 v1, v14, 0x3c000000, v216
	v_rsq_f32_e32 v1, v1
	v_mul_f32_e32 v9, v9, v76
	v_bfe_u32 v10, v9, 16, 1
	v_add3_u32 v9, v9, v10, s60
	v_mul_f32_e32 v8, v53, v1
	v_mul_f32_e32 v8, v8, v74
	global_store_short_d16_hi v[28:29], v9, off offset:3200
	v_bfe_u32 v9, v8, 16, 1
	v_add3_u32 v8, v8, v9, s60
	global_store_short_d16_hi v[2:3], v8, off
	v_mul_f32_e32 v8, v36, v1
	v_mul_f32_e32 v8, v8, v75
	v_bfe_u32 v9, v8, 16, 1
	v_add3_u32 v8, v8, v9, s60
	global_store_short_d16_hi v[2:3], v8, off offset:64
	v_mul_f32_e32 v8, v21, v1
	v_mul_f32_e32 v1, v7, v1
	v_mul_f32_e32 v1, v1, v77
	v_bfe_u32 v7, v1, 16, 1
	v_add3_u32 v1, v1, v7, s60
	global_store_short_d16_hi v[2:3], v1, off offset:192
	v_fmamk_f32 v1, v13, 0x3c000000, v216
	v_rsq_f32_e32 v1, v1
	v_mul_f32_e32 v8, v8, v76
	v_bfe_u32 v9, v8, 16, 1
	v_add3_u32 v8, v8, v9, s60
	v_mul_f32_e32 v7, v52, v1
	v_mul_f32_e32 v7, v7, v74
	global_store_short_d16_hi v[2:3], v8, off offset:128
	v_bfe_u32 v8, v7, 16, 1
	v_add3_u32 v7, v7, v8, s60
	global_store_short_d16_hi v[2:3], v7, off offset:1024
	v_mul_f32_e32 v7, v34, v1
	v_mul_f32_e32 v7, v7, v75
	v_bfe_u32 v8, v7, 16, 1
	v_add3_u32 v7, v7, v8, s60
	global_store_short_d16_hi v[2:3], v7, off offset:1088
	v_mul_f32_e32 v7, v19, v1
	v_mul_f32_e32 v1, v6, v1
	v_mul_f32_e32 v1, v1, v77
	v_bfe_u32 v6, v1, 16, 1
	v_add3_u32 v1, v1, v6, s60
	global_store_short_d16_hi v[2:3], v1, off offset:1216
	v_fmamk_f32 v1, v12, 0x3c000000, v216
	v_rsq_f32_e32 v1, v1
	v_mul_f32_e32 v7, v7, v76
	v_bfe_u32 v8, v7, 16, 1
	v_add3_u32 v7, v7, v8, s60
	v_mul_f32_e32 v6, v51, v1
	v_mul_f32_e32 v6, v6, v74
	global_store_short_d16_hi v[2:3], v7, off offset:1152
	v_bfe_u32 v7, v6, 16, 1
	v_add3_u32 v6, v6, v7, s60
	global_store_short_d16_hi v[2:3], v6, off offset:2048
	v_mul_f32_e32 v6, v37, v1
	v_mul_f32_e32 v6, v6, v75
	v_bfe_u32 v7, v6, 16, 1
	v_add3_u32 v6, v6, v7, s60
	global_store_short_d16_hi v[2:3], v6, off offset:2112
	v_mul_f32_e32 v6, v20, v1
	v_mul_f32_e32 v1, v5, v1
	v_mul_f32_e32 v1, v1, v77
	v_bfe_u32 v5, v1, 16, 1
	v_add3_u32 v1, v1, v5, s60
	global_store_short_d16_hi v[2:3], v1, off offset:2240
	v_fmamk_f32 v1, v11, 0x3c000000, v216
	v_rsq_f32_e32 v1, v1
	v_mul_f32_e32 v6, v6, v76
	v_bfe_u32 v7, v6, 16, 1
	v_add3_u32 v6, v6, v7, s60
	v_mul_f32_e32 v5, v50, v1
	v_mul_f32_e32 v5, v74, v5
	global_store_short_d16_hi v[2:3], v6, off offset:2176
	v_bfe_u32 v6, v5, 16, 1
	v_add3_u32 v5, v5, v6, s60
	global_store_short_d16_hi v[2:3], v5, off offset:3072
	v_mul_f32_e32 v5, v35, v1
	v_mul_f32_e32 v5, v75, v5
	v_bfe_u32 v6, v5, 16, 1
	v_add3_u32 v5, v5, v6, s60
	global_store_short_d16_hi v[2:3], v5, off offset:3136
	v_mul_f32_e32 v5, v18, v1
	v_mul_f32_e32 v1, v4, v1
	v_mul_f32_e32 v5, v76, v5
	v_mul_f32_e32 v1, v77, v1
	v_bfe_u32 v6, v5, 16, 1
	v_bfe_u32 v4, v1, 16, 1
	v_add3_u32 v5, v5, v6, s60
	v_add3_u32 v1, v1, v4, s60
	global_store_short_d16_hi v[2:3], v5, off offset:3200
	global_store_short_d16_hi v[2:3], v1, off offset:3264
	s_branch .LBB0_389
